# top-16 selection via pure-VALU rank counting against LDS-broadcast keys (no SGPR round trips), exact same selection; plus P0 load batching, packed gate epilogue, batched unit-epilogue loads
# baseline (speedup 1.0000x reference)
; __device__ __forceinline__ void nsa_unit(int b, int qt, const bf16_t* proj, const bf16_t* vt, const bf16_t* kc, const bf16_t* vcT, bf16_t* ab0, LAS unsigned char* lds, int tid, int wid, int lane) {
;     ...
;       const bool valid = lane <= qt, forced = (lane == 0) || (lane == qt) || (lane == qt - 1);
;       float val = ((imp0[qi * 65 + lane] * linvL[qi] + imp1[qi * 65 + lane] * linvL[64 + qi]) + imp2[qi * 65 + lane] * linvL[128 + qi]) + imp3[qi * 65 + lane] * linvL[192 + qi];
;       val = valid ? (forced ? val + 1.0e4f : val) : -1.0e30f;
;       int rank = 0;
; #pragma unroll 4
;       for (int jj = 0; jj < 64; ++jj) {
;         const float o = __builtin_bit_cast(float, __builtin_amdgcn_readlane(__builtin_bit_cast(int, val), jj));
;         rank += (o > val || (o == val && jj < lane)) ? 1 : 0;
;       }
.LBB0_689:
	s_or_b64 exec, exec, s[14:15]
	v_max_i32_e32 v250, -1, v0
	s_lshl_b32 s97, s78, 5
	s_add_i32 s97, s97, 0x8200
	v_add_u32_e32 v251, s97, v141
	v_mov_b32_e32 v252, s97
	ds_write_b32 v251, v250
	v_mov_b32_e32 v40, 0
	v_mov_b32_e32 v41, 0
	v_mov_b32_e32 v42, 0
	v_mov_b32_e32 v43, 0
	ds_read_b128 v[234:237], v252
	ds_read_b128 v[238:241], v252 offset:16
	ds_read_b128 v[242:245], v252 offset:32
	ds_read_b128 v[246:249], v252 offset:48
	s_waitcnt lgkmcnt(3)
	v_sub_u32_e32 v36, v250, v234
	v_sub_u32_e32 v37, v250, v235
	v_sub_u32_e32 v38, v250, v236
	v_sub_u32_e32 v39, v250, v237
	ds_read_b128 v[234:237], v252 offset:64
	v_ashrrev_i32_e32 v36, 31, v36
	v_ashrrev_i32_e32 v37, 31, v37
	v_ashrrev_i32_e32 v38, 31, v38
	v_ashrrev_i32_e32 v39, 31, v39
	v_sub_u32_e32 v40, v40, v36
	v_sub_u32_e32 v41, v41, v37
	v_sub_u32_e32 v42, v42, v38
	v_sub_u32_e32 v43, v43, v39
	s_waitcnt lgkmcnt(3)
	v_sub_u32_e32 v36, v250, v238
	v_sub_u32_e32 v37, v250, v239
	v_sub_u32_e32 v38, v250, v240
	v_sub_u32_e32 v39, v250, v241
	ds_read_b128 v[238:241], v252 offset:80
	v_ashrrev_i32_e32 v36, 31, v36
	v_ashrrev_i32_e32 v37, 31, v37
	v_ashrrev_i32_e32 v38, 31, v38
	v_ashrrev_i32_e32 v39, 31, v39
	v_sub_u32_e32 v40, v40, v36
	v_sub_u32_e32 v41, v41, v37
	v_sub_u32_e32 v42, v42, v38
	v_sub_u32_e32 v43, v43, v39
	s_waitcnt lgkmcnt(3)
	v_sub_u32_e32 v36, v250, v242
	v_sub_u32_e32 v37, v250, v243
	v_sub_u32_e32 v38, v250, v244
	v_sub_u32_e32 v39, v250, v245
	ds_read_b128 v[242:245], v252 offset:96
	v_ashrrev_i32_e32 v36, 31, v36
	v_ashrrev_i32_e32 v37, 31, v37
	v_ashrrev_i32_e32 v38, 31, v38
	v_ashrrev_i32_e32 v39, 31, v39
	v_sub_u32_e32 v40, v40, v36
	v_sub_u32_e32 v41, v41, v37
	v_sub_u32_e32 v42, v42, v38
	v_sub_u32_e32 v43, v43, v39
	s_waitcnt lgkmcnt(3)
	v_sub_u32_e32 v36, v250, v246
	v_sub_u32_e32 v37, v250, v247
	v_sub_u32_e32 v38, v250, v248
	v_sub_u32_e32 v39, v250, v249
	ds_read_b128 v[246:249], v252 offset:112
	v_ashrrev_i32_e32 v36, 31, v36
	v_ashrrev_i32_e32 v37, 31, v37
	v_ashrrev_i32_e32 v38, 31, v38
	v_ashrrev_i32_e32 v39, 31, v39
	v_sub_u32_e32 v40, v40, v36
	v_sub_u32_e32 v41, v41, v37
	v_sub_u32_e32 v42, v42, v38
	v_sub_u32_e32 v43, v43, v39
	s_waitcnt lgkmcnt(3)
	v_sub_u32_e32 v36, v250, v234
	v_sub_u32_e32 v37, v250, v235
	v_sub_u32_e32 v38, v250, v236
	v_sub_u32_e32 v39, v250, v237
	ds_read_b128 v[234:237], v252 offset:128
	v_ashrrev_i32_e32 v36, 31, v36
	v_ashrrev_i32_e32 v37, 31, v37
	v_ashrrev_i32_e32 v38, 31, v38
	v_ashrrev_i32_e32 v39, 31, v39
	v_sub_u32_e32 v40, v40, v36
	v_sub_u32_e32 v41, v41, v37
	v_sub_u32_e32 v42, v42, v38
	v_sub_u32_e32 v43, v43, v39
	s_waitcnt lgkmcnt(3)
	v_sub_u32_e32 v36, v250, v238
	v_sub_u32_e32 v37, v250, v239
	v_sub_u32_e32 v38, v250, v240
	v_sub_u32_e32 v39, v250, v241
	ds_read_b128 v[238:241], v252 offset:144
	v_ashrrev_i32_e32 v36, 31, v36
	v_ashrrev_i32_e32 v37, 31, v37
	v_ashrrev_i32_e32 v38, 31, v38
	v_ashrrev_i32_e32 v39, 31, v39
	v_sub_u32_e32 v40, v40, v36
	v_sub_u32_e32 v41, v41, v37
	v_sub_u32_e32 v42, v42, v38
	v_sub_u32_e32 v43, v43, v39
	s_waitcnt lgkmcnt(3)
	v_sub_u32_e32 v36, v250, v242
	v_sub_u32_e32 v37, v250, v243
	v_sub_u32_e32 v38, v250, v244
	v_sub_u32_e32 v39, v250, v245
	ds_read_b128 v[242:245], v252 offset:160
	v_ashrrev_i32_e32 v36, 31, v36
	v_ashrrev_i32_e32 v37, 31, v37
	v_ashrrev_i32_e32 v38, 31, v38
	v_ashrrev_i32_e32 v39, 31, v39
	v_sub_u32_e32 v40, v40, v36
	v_sub_u32_e32 v41, v41, v37
	v_sub_u32_e32 v42, v42, v38
	v_sub_u32_e32 v43, v43, v39
	s_waitcnt lgkmcnt(3)
	v_sub_u32_e32 v36, v250, v246
	v_sub_u32_e32 v37, v250, v247
	v_sub_u32_e32 v38, v250, v248
	v_sub_u32_e32 v39, v250, v249
	ds_read_b128 v[246:249], v252 offset:176
	v_ashrrev_i32_e32 v36, 31, v36
	v_ashrrev_i32_e32 v37, 31, v37
	v_ashrrev_i32_e32 v38, 31, v38
	v_ashrrev_i32_e32 v39, 31, v39
	v_sub_u32_e32 v40, v40, v36
	v_sub_u32_e32 v41, v41, v37
	v_sub_u32_e32 v42, v42, v38
	v_sub_u32_e32 v43, v43, v39
	s_waitcnt lgkmcnt(3)
; __device__ __forceinline__ void nsa_unit(int b, int qt, const bf16_t* proj, const bf16_t* vt, const bf16_t* kc, const bf16_t* vcT, bf16_t* ab0, LAS unsigned char* lds, int tid, int wid, int lane) {
;     ...
;       int rank = 0;
; #pragma unroll 4
;       for (int jj = 0; jj < 64; ++jj) {
;         const float o = __builtin_bit_cast(float, __builtin_amdgcn_readlane(__builtin_bit_cast(int, val), jj));
;         rank += (o > val || (o == val && jj < lane)) ? 1 : 0;
;       }
;       const unsigned long long mk = __ballot(rank < 16);
;       if (lane == 0) { selw[qi * 2] = (unsigned)mk; selw[qi * 2 + 1] = (unsigned)(mk >> 32); }
	v_sub_u32_e32 v36, v250, v234
	v_sub_u32_e32 v37, v250, v235
	v_sub_u32_e32 v38, v250, v236
	v_sub_u32_e32 v39, v250, v237
	ds_read_b128 v[234:237], v252 offset:192
	v_ashrrev_i32_e32 v36, 31, v36
	v_ashrrev_i32_e32 v37, 31, v37
	v_ashrrev_i32_e32 v38, 31, v38
	v_ashrrev_i32_e32 v39, 31, v39
	v_sub_u32_e32 v40, v40, v36
	v_sub_u32_e32 v41, v41, v37
	v_sub_u32_e32 v42, v42, v38
	v_sub_u32_e32 v43, v43, v39
	s_waitcnt lgkmcnt(3)
	v_sub_u32_e32 v36, v250, v238
	v_sub_u32_e32 v37, v250, v239
	v_sub_u32_e32 v38, v250, v240
	v_sub_u32_e32 v39, v250, v241
	ds_read_b128 v[238:241], v252 offset:208
	v_ashrrev_i32_e32 v36, 31, v36
	v_ashrrev_i32_e32 v37, 31, v37
	v_ashrrev_i32_e32 v38, 31, v38
	v_ashrrev_i32_e32 v39, 31, v39
	v_sub_u32_e32 v40, v40, v36
	v_sub_u32_e32 v41, v41, v37
	v_sub_u32_e32 v42, v42, v38
	v_sub_u32_e32 v43, v43, v39
	s_waitcnt lgkmcnt(3)
	v_sub_u32_e32 v36, v250, v242
	v_sub_u32_e32 v37, v250, v243
	v_sub_u32_e32 v38, v250, v244
	v_sub_u32_e32 v39, v250, v245
	ds_read_b128 v[242:245], v252 offset:224
	v_ashrrev_i32_e32 v36, 31, v36
	v_ashrrev_i32_e32 v37, 31, v37
	v_ashrrev_i32_e32 v38, 31, v38
	v_ashrrev_i32_e32 v39, 31, v39
	v_sub_u32_e32 v40, v40, v36
	v_sub_u32_e32 v41, v41, v37
	v_sub_u32_e32 v42, v42, v38
	v_sub_u32_e32 v43, v43, v39
	s_waitcnt lgkmcnt(3)
	v_sub_u32_e32 v36, v250, v246
	v_sub_u32_e32 v37, v250, v247
	v_sub_u32_e32 v38, v250, v248
	v_sub_u32_e32 v39, v250, v249
	ds_read_b128 v[246:249], v252 offset:240
	v_ashrrev_i32_e32 v36, 31, v36
	v_ashrrev_i32_e32 v37, 31, v37
	v_ashrrev_i32_e32 v38, 31, v38
	v_ashrrev_i32_e32 v39, 31, v39
	v_sub_u32_e32 v40, v40, v36
	v_sub_u32_e32 v41, v41, v37
	v_sub_u32_e32 v42, v42, v38
	v_sub_u32_e32 v43, v43, v39
	s_waitcnt lgkmcnt(3)
	v_sub_u32_e32 v36, v250, v234
	v_sub_u32_e32 v37, v250, v235
	v_sub_u32_e32 v38, v250, v236
	v_sub_u32_e32 v39, v250, v237
	v_ashrrev_i32_e32 v36, 31, v36
	v_ashrrev_i32_e32 v37, 31, v37
	v_ashrrev_i32_e32 v38, 31, v38
	v_ashrrev_i32_e32 v39, 31, v39
	v_sub_u32_e32 v40, v40, v36
	v_sub_u32_e32 v41, v41, v37
	v_sub_u32_e32 v42, v42, v38
	v_sub_u32_e32 v43, v43, v39
	s_waitcnt lgkmcnt(2)
	v_sub_u32_e32 v36, v250, v238
	v_sub_u32_e32 v37, v250, v239
	v_sub_u32_e32 v38, v250, v240
	v_sub_u32_e32 v39, v250, v241
	v_ashrrev_i32_e32 v36, 31, v36
	v_ashrrev_i32_e32 v37, 31, v37
	v_ashrrev_i32_e32 v38, 31, v38
	v_ashrrev_i32_e32 v39, 31, v39
	v_sub_u32_e32 v40, v40, v36
	v_sub_u32_e32 v41, v41, v37
	v_sub_u32_e32 v42, v42, v38
	v_sub_u32_e32 v43, v43, v39
	s_waitcnt lgkmcnt(1)
	v_sub_u32_e32 v36, v250, v242
	v_sub_u32_e32 v37, v250, v243
	v_sub_u32_e32 v38, v250, v244
	v_sub_u32_e32 v39, v250, v245
	v_ashrrev_i32_e32 v36, 31, v36
	v_ashrrev_i32_e32 v37, 31, v37
	v_ashrrev_i32_e32 v38, 31, v38
	v_ashrrev_i32_e32 v39, 31, v39
	v_sub_u32_e32 v40, v40, v36
	v_sub_u32_e32 v41, v41, v37
	v_sub_u32_e32 v42, v42, v38
	v_sub_u32_e32 v43, v43, v39
	s_waitcnt lgkmcnt(0)
	v_sub_u32_e32 v36, v250, v246
	v_sub_u32_e32 v37, v250, v247
	v_sub_u32_e32 v38, v250, v248
	v_sub_u32_e32 v39, v250, v249
	v_ashrrev_i32_e32 v36, 31, v36
	v_ashrrev_i32_e32 v37, 31, v37
	v_ashrrev_i32_e32 v38, 31, v38
	v_ashrrev_i32_e32 v39, 31, v39
	v_sub_u32_e32 v40, v40, v36
	v_sub_u32_e32 v41, v41, v37
	v_sub_u32_e32 v42, v42, v38
	v_sub_u32_e32 v43, v43, v39
	v_add3_u32 v40, v40, v41, v42
	v_add_u32_e32 v40, v40, v43
	v_cmp_gt_u32_e64 s[16:17], 16, v40
	s_bcnt1_i32_b64 s14, s[16:17]
	s_cmp_eq_u32 s14, 16
	s_cbranch_scc1 .Ltk4_l0_done
	s_mov_b32 s97, 15
.Ltk4_l0_find:
	v_cmp_eq_u32_e64 s[18:19], s97, v40
	s_and_b64 s[18:19], s[18:19], s[16:17]
	s_cmp_lg_u64 s[18:19], 0
	s_cbranch_scc1 .Ltk4_l0_found
	s_sub_i32 s97, s97, 1
	s_branch .Ltk4_l0_find
.Ltk4_l0_found:
	s_andn2_b64 s[16:17], s[16:17], s[18:19]
	s_sub_i32 s97, 16, s97
.Ltk4_l0_tie:
	s_ff1_i32_b64 s14, s[18:19]
	s_bitset1_b64 s[16:17], s14
	s_bitset0_b64 s[18:19], s14
	s_sub_i32 s97, s97, 1
	s_cmp_lg_u32 s97, 0
	s_cbranch_scc1 .Ltk4_l0_tie
.Ltk4_l0_done:
	s_and_saveexec_b64 s[14:15], s[4:5]
	s_cbranch_execz .LBB0_686
	s_lshl_b32 s18, s95, 3
	s_add_i32 s18, s18, 0
	s_add_i32 s18, s18, 0x1f500
	v_mov_b32_e32 v0, s18
	v_mov_b64_e32 v[36:37], s[16:17]
	ds_write_b64 v0, v[36:37]
	s_branch .LBB0_686

; __device__ __forceinline__ void nsa_unit(int b, int qt, const bf16_t* proj, const bf16_t* vt, const bf16_t* kc, const bf16_t* vcT, bf16_t* ab0, LAS unsigned char* lds, int tid, int wid, int lane) {
;     ...
;       const bool valid = lane <= qt, forced = (lane == 0) || (lane == qt) || (lane == qt - 1);
;       float val = ((imp0[qi * 65 + lane] * linvL[qi] + imp1[qi * 65 + lane] * linvL[64 + qi]) + imp2[qi * 65 + lane] * linvL[128 + qi]) + imp3[qi * 65 + lane] * linvL[192 + qi];
;       val = valid ? (forced ? val + 1.0e4f : val) : -1.0e30f;
;       int rank = 0;
; #pragma unroll 4
;       for (int jj = 0; jj < 64; ++jj) {
;         const float o = __builtin_bit_cast(float, __builtin_amdgcn_readlane(__builtin_bit_cast(int, val), jj));
;         rank += (o > val || (o == val && jj < lane)) ? 1 : 0;
;       }
.LBB0_1526:
	s_or_b64 exec, exec, s[14:15]
	v_max_i32_e32 v250, -1, v0
	s_lshl_b32 s78, s57, 5
	s_add_i32 s78, s78, 0x8200
	v_add_u32_e32 v251, s78, v141
	v_mov_b32_e32 v252, s78
	ds_write_b32 v251, v250
	v_mov_b32_e32 v40, 0
	v_mov_b32_e32 v41, 0
	v_mov_b32_e32 v42, 0
	v_mov_b32_e32 v43, 0
	ds_read_b128 v[234:237], v252
	ds_read_b128 v[238:241], v252 offset:16
	ds_read_b128 v[242:245], v252 offset:32
	ds_read_b128 v[246:249], v252 offset:48
	s_waitcnt lgkmcnt(3)
	v_sub_u32_e32 v36, v250, v234
	v_sub_u32_e32 v37, v250, v235
	v_sub_u32_e32 v38, v250, v236
	v_sub_u32_e32 v39, v250, v237
	ds_read_b128 v[234:237], v252 offset:64
	v_ashrrev_i32_e32 v36, 31, v36
	v_ashrrev_i32_e32 v37, 31, v37
	v_ashrrev_i32_e32 v38, 31, v38
	v_ashrrev_i32_e32 v39, 31, v39
	v_sub_u32_e32 v40, v40, v36
	v_sub_u32_e32 v41, v41, v37
	v_sub_u32_e32 v42, v42, v38
	v_sub_u32_e32 v43, v43, v39
	s_waitcnt lgkmcnt(3)
	v_sub_u32_e32 v36, v250, v238
	v_sub_u32_e32 v37, v250, v239
	v_sub_u32_e32 v38, v250, v240
	v_sub_u32_e32 v39, v250, v241
	ds_read_b128 v[238:241], v252 offset:80
	v_ashrrev_i32_e32 v36, 31, v36
	v_ashrrev_i32_e32 v37, 31, v37
	v_ashrrev_i32_e32 v38, 31, v38
	v_ashrrev_i32_e32 v39, 31, v39
	v_sub_u32_e32 v40, v40, v36
	v_sub_u32_e32 v41, v41, v37
	v_sub_u32_e32 v42, v42, v38
	v_sub_u32_e32 v43, v43, v39
	s_waitcnt lgkmcnt(3)
	v_sub_u32_e32 v36, v250, v242
	v_sub_u32_e32 v37, v250, v243
	v_sub_u32_e32 v38, v250, v244
	v_sub_u32_e32 v39, v250, v245
	ds_read_b128 v[242:245], v252 offset:96
	v_ashrrev_i32_e32 v36, 31, v36
	v_ashrrev_i32_e32 v37, 31, v37
	v_ashrrev_i32_e32 v38, 31, v38
	v_ashrrev_i32_e32 v39, 31, v39
	v_sub_u32_e32 v40, v40, v36
	v_sub_u32_e32 v41, v41, v37
	v_sub_u32_e32 v42, v42, v38
	v_sub_u32_e32 v43, v43, v39
	s_waitcnt lgkmcnt(3)
	v_sub_u32_e32 v36, v250, v246
	v_sub_u32_e32 v37, v250, v247
	v_sub_u32_e32 v38, v250, v248
	v_sub_u32_e32 v39, v250, v249
	ds_read_b128 v[246:249], v252 offset:112
	v_ashrrev_i32_e32 v36, 31, v36
	v_ashrrev_i32_e32 v37, 31, v37
	v_ashrrev_i32_e32 v38, 31, v38
	v_ashrrev_i32_e32 v39, 31, v39
	v_sub_u32_e32 v40, v40, v36
	v_sub_u32_e32 v41, v41, v37
	v_sub_u32_e32 v42, v42, v38
	v_sub_u32_e32 v43, v43, v39
	s_waitcnt lgkmcnt(3)
	v_sub_u32_e32 v36, v250, v234
	v_sub_u32_e32 v37, v250, v235
	v_sub_u32_e32 v38, v250, v236
	v_sub_u32_e32 v39, v250, v237
	ds_read_b128 v[234:237], v252 offset:128
	v_ashrrev_i32_e32 v36, 31, v36
	v_ashrrev_i32_e32 v37, 31, v37
	v_ashrrev_i32_e32 v38, 31, v38
	v_ashrrev_i32_e32 v39, 31, v39
	v_sub_u32_e32 v40, v40, v36
	v_sub_u32_e32 v41, v41, v37
	v_sub_u32_e32 v42, v42, v38
	v_sub_u32_e32 v43, v43, v39
	s_waitcnt lgkmcnt(3)
	v_sub_u32_e32 v36, v250, v238
	v_sub_u32_e32 v37, v250, v239
	v_sub_u32_e32 v38, v250, v240
	v_sub_u32_e32 v39, v250, v241
	ds_read_b128 v[238:241], v252 offset:144
	v_ashrrev_i32_e32 v36, 31, v36
	v_ashrrev_i32_e32 v37, 31, v37
	v_ashrrev_i32_e32 v38, 31, v38
	v_ashrrev_i32_e32 v39, 31, v39
	v_sub_u32_e32 v40, v40, v36
	v_sub_u32_e32 v41, v41, v37
	v_sub_u32_e32 v42, v42, v38
	v_sub_u32_e32 v43, v43, v39
	s_waitcnt lgkmcnt(3)
	v_sub_u32_e32 v36, v250, v242
	v_sub_u32_e32 v37, v250, v243
	v_sub_u32_e32 v38, v250, v244
	v_sub_u32_e32 v39, v250, v245
	ds_read_b128 v[242:245], v252 offset:160
	v_ashrrev_i32_e32 v36, 31, v36
	v_ashrrev_i32_e32 v37, 31, v37
	v_ashrrev_i32_e32 v38, 31, v38
	v_ashrrev_i32_e32 v39, 31, v39
	v_sub_u32_e32 v40, v40, v36
	v_sub_u32_e32 v41, v41, v37
	v_sub_u32_e32 v42, v42, v38
	v_sub_u32_e32 v43, v43, v39
	s_waitcnt lgkmcnt(3)
	v_sub_u32_e32 v36, v250, v246
	v_sub_u32_e32 v37, v250, v247
	v_sub_u32_e32 v38, v250, v248
	v_sub_u32_e32 v39, v250, v249
	ds_read_b128 v[246:249], v252 offset:176
	v_ashrrev_i32_e32 v36, 31, v36
	v_ashrrev_i32_e32 v37, 31, v37
	v_ashrrev_i32_e32 v38, 31, v38
	v_ashrrev_i32_e32 v39, 31, v39
	v_sub_u32_e32 v40, v40, v36
	v_sub_u32_e32 v41, v41, v37
	v_sub_u32_e32 v42, v42, v38
	v_sub_u32_e32 v43, v43, v39
	s_waitcnt lgkmcnt(3)
; __device__ __forceinline__ void nsa_unit(int b, int qt, const bf16_t* proj, const bf16_t* vt, const bf16_t* kc, const bf16_t* vcT, bf16_t* ab0, LAS unsigned char* lds, int tid, int wid, int lane) {
;     ...
;       int rank = 0;
; #pragma unroll 4
;       for (int jj = 0; jj < 64; ++jj) {
;         const float o = __builtin_bit_cast(float, __builtin_amdgcn_readlane(__builtin_bit_cast(int, val), jj));
;         rank += (o > val || (o == val && jj < lane)) ? 1 : 0;
;       }
;       const unsigned long long mk = __ballot(rank < 16);
;       if (lane == 0) { selw[qi * 2] = (unsigned)mk; selw[qi * 2 + 1] = (unsigned)(mk >> 32); }
	v_sub_u32_e32 v36, v250, v234
	v_sub_u32_e32 v37, v250, v235
	v_sub_u32_e32 v38, v250, v236
	v_sub_u32_e32 v39, v250, v237
	ds_read_b128 v[234:237], v252 offset:192
	v_ashrrev_i32_e32 v36, 31, v36
	v_ashrrev_i32_e32 v37, 31, v37
	v_ashrrev_i32_e32 v38, 31, v38
	v_ashrrev_i32_e32 v39, 31, v39
	v_sub_u32_e32 v40, v40, v36
	v_sub_u32_e32 v41, v41, v37
	v_sub_u32_e32 v42, v42, v38
	v_sub_u32_e32 v43, v43, v39
	s_waitcnt lgkmcnt(3)
	v_sub_u32_e32 v36, v250, v238
	v_sub_u32_e32 v37, v250, v239
	v_sub_u32_e32 v38, v250, v240
	v_sub_u32_e32 v39, v250, v241
	ds_read_b128 v[238:241], v252 offset:208
	v_ashrrev_i32_e32 v36, 31, v36
	v_ashrrev_i32_e32 v37, 31, v37
	v_ashrrev_i32_e32 v38, 31, v38
	v_ashrrev_i32_e32 v39, 31, v39
	v_sub_u32_e32 v40, v40, v36
	v_sub_u32_e32 v41, v41, v37
	v_sub_u32_e32 v42, v42, v38
	v_sub_u32_e32 v43, v43, v39
	s_waitcnt lgkmcnt(3)
	v_sub_u32_e32 v36, v250, v242
	v_sub_u32_e32 v37, v250, v243
	v_sub_u32_e32 v38, v250, v244
	v_sub_u32_e32 v39, v250, v245
	ds_read_b128 v[242:245], v252 offset:224
	v_ashrrev_i32_e32 v36, 31, v36
	v_ashrrev_i32_e32 v37, 31, v37
	v_ashrrev_i32_e32 v38, 31, v38
	v_ashrrev_i32_e32 v39, 31, v39
	v_sub_u32_e32 v40, v40, v36
	v_sub_u32_e32 v41, v41, v37
	v_sub_u32_e32 v42, v42, v38
	v_sub_u32_e32 v43, v43, v39
	s_waitcnt lgkmcnt(3)
	v_sub_u32_e32 v36, v250, v246
	v_sub_u32_e32 v37, v250, v247
	v_sub_u32_e32 v38, v250, v248
	v_sub_u32_e32 v39, v250, v249
	ds_read_b128 v[246:249], v252 offset:240
	v_ashrrev_i32_e32 v36, 31, v36
	v_ashrrev_i32_e32 v37, 31, v37
	v_ashrrev_i32_e32 v38, 31, v38
	v_ashrrev_i32_e32 v39, 31, v39
	v_sub_u32_e32 v40, v40, v36
	v_sub_u32_e32 v41, v41, v37
	v_sub_u32_e32 v42, v42, v38
	v_sub_u32_e32 v43, v43, v39
	s_waitcnt lgkmcnt(3)
	v_sub_u32_e32 v36, v250, v234
	v_sub_u32_e32 v37, v250, v235
	v_sub_u32_e32 v38, v250, v236
	v_sub_u32_e32 v39, v250, v237
	v_ashrrev_i32_e32 v36, 31, v36
	v_ashrrev_i32_e32 v37, 31, v37
	v_ashrrev_i32_e32 v38, 31, v38
	v_ashrrev_i32_e32 v39, 31, v39
	v_sub_u32_e32 v40, v40, v36
	v_sub_u32_e32 v41, v41, v37
	v_sub_u32_e32 v42, v42, v38
	v_sub_u32_e32 v43, v43, v39
	s_waitcnt lgkmcnt(2)
	v_sub_u32_e32 v36, v250, v238
	v_sub_u32_e32 v37, v250, v239
	v_sub_u32_e32 v38, v250, v240
	v_sub_u32_e32 v39, v250, v241
	v_ashrrev_i32_e32 v36, 31, v36
	v_ashrrev_i32_e32 v37, 31, v37
	v_ashrrev_i32_e32 v38, 31, v38
	v_ashrrev_i32_e32 v39, 31, v39
	v_sub_u32_e32 v40, v40, v36
	v_sub_u32_e32 v41, v41, v37
	v_sub_u32_e32 v42, v42, v38
	v_sub_u32_e32 v43, v43, v39
	s_waitcnt lgkmcnt(1)
	v_sub_u32_e32 v36, v250, v242
	v_sub_u32_e32 v37, v250, v243
	v_sub_u32_e32 v38, v250, v244
	v_sub_u32_e32 v39, v250, v245
	v_ashrrev_i32_e32 v36, 31, v36
	v_ashrrev_i32_e32 v37, 31, v37
	v_ashrrev_i32_e32 v38, 31, v38
	v_ashrrev_i32_e32 v39, 31, v39
	v_sub_u32_e32 v40, v40, v36
	v_sub_u32_e32 v41, v41, v37
	v_sub_u32_e32 v42, v42, v38
	v_sub_u32_e32 v43, v43, v39
	s_waitcnt lgkmcnt(0)
	v_sub_u32_e32 v36, v250, v246
	v_sub_u32_e32 v37, v250, v247
	v_sub_u32_e32 v38, v250, v248
	v_sub_u32_e32 v39, v250, v249
	v_ashrrev_i32_e32 v36, 31, v36
	v_ashrrev_i32_e32 v37, 31, v37
	v_ashrrev_i32_e32 v38, 31, v38
	v_ashrrev_i32_e32 v39, 31, v39
	v_sub_u32_e32 v40, v40, v36
	v_sub_u32_e32 v41, v41, v37
	v_sub_u32_e32 v42, v42, v38
	v_sub_u32_e32 v43, v43, v39
	v_add3_u32 v40, v40, v41, v42
	v_add_u32_e32 v40, v40, v43
	v_cmp_gt_u32_e64 s[16:17], 16, v40
	s_bcnt1_i32_b64 s14, s[16:17]
	s_cmp_eq_u32 s14, 16
	s_cbranch_scc1 .Ltk4_l1_done
	s_mov_b32 s78, 15
.Ltk4_l1_find:
	v_cmp_eq_u32_e64 s[18:19], s78, v40
	s_and_b64 s[18:19], s[18:19], s[16:17]
	s_cmp_lg_u64 s[18:19], 0
	s_cbranch_scc1 .Ltk4_l1_found
	s_sub_i32 s78, s78, 1
	s_branch .Ltk4_l1_find
.Ltk4_l1_found:
	s_andn2_b64 s[16:17], s[16:17], s[18:19]
	s_sub_i32 s78, 16, s78
.Ltk4_l1_tie:
	s_ff1_i32_b64 s14, s[18:19]
	s_bitset1_b64 s[16:17], s14
	s_bitset0_b64 s[18:19], s14
	s_sub_i32 s78, s78, 1
	s_cmp_lg_u32 s78, 0
	s_cbranch_scc1 .Ltk4_l1_tie
.Ltk4_l1_done:
	s_and_saveexec_b64 s[14:15], s[4:5]
	s_cbranch_execz .LBB0_1523
	s_lshl_b32 s18, s77, 3
	s_add_i32 s18, s18, 0
	s_add_i32 s18, s18, 0x1f500
	v_mov_b32_e32 v0, s18
	v_mov_b64_e32 v[36:37], s[16:17]
	ds_write_b64 v0, v[36:37]
	s_branch .LBB0_1523
